# MLA: tile prefetch addresses as scalar base + lane offset (scalar increments), LDS write addresses precomputed
# speedup vs baseline: 1.0026x; 1.0026x over previous
.LBB0_619:
	v_readfirstlane_b32 s12, v170
	s_lshr_b32 s12, s12, 6
	s_mul_i32 s12, s12, 12288
	s_add_i32 s12, s12, 45056
	v_and_b32_e32 v172, 63, v170
	v_lshl_add_u32 v172, v172, 2, s12
	ds_write_b32 v172, v202 offset:0
	ds_write_b32 v172, v203 offset:256
	ds_write_b32 v172, v204 offset:512
	ds_write_b32 v172, v205 offset:768
	ds_write_b32 v172, v206 offset:1024
	ds_write_b32 v172, v207 offset:1280
	ds_write_b32 v172, v208 offset:1536
	ds_write_b32 v172, v209 offset:1792
	ds_write_b32 v172, v210 offset:2048
	ds_write_b32 v172, v211 offset:2304
	ds_write_b32 v172, v212 offset:2560
	ds_write_b32 v172, v213 offset:2816
	ds_write_b32 v172, v214 offset:3072
	ds_write_b32 v172, v215 offset:3328
	ds_write_b32 v172, v216 offset:3584
	ds_write_b32 v172, v217 offset:3840
	ds_write_b32 v172, v218 offset:4096
	ds_write_b32 v172, v219 offset:4352
	ds_write_b32 v172, v220 offset:4608
	ds_write_b32 v172, v221 offset:4864
	ds_write_b32 v172, v222 offset:5120
	ds_write_b32 v172, v223 offset:5376
	ds_write_b32 v172, v224 offset:5632
	ds_write_b32 v172, v225 offset:5888
	ds_write_b32 v172, v226 offset:6144
	ds_write_b32 v172, v227 offset:6400
	ds_write_b32 v172, v228 offset:6656
	ds_write_b32 v172, v229 offset:6912
	ds_write_b32 v172, v230 offset:7168
	ds_write_b32 v172, v231 offset:7424
	ds_write_b32 v172, v232 offset:7680
	ds_write_b32 v172, v233 offset:7936
	ds_write_b32 v172, v234 offset:8192
	ds_write_b32 v172, v235 offset:8448
	ds_write_b32 v172, v236 offset:8704
	ds_write_b32 v172, v237 offset:8960
	ds_write_b32 v172, v238 offset:9216
	ds_write_b32 v172, v239 offset:9472
	ds_write_b32 v172, v240 offset:9728
	ds_write_b32 v172, v241 offset:9984
	ds_write_b32 v172, v242 offset:10240
	ds_write_b32 v172, v243 offset:10496
	ds_write_b32 v172, v244 offset:10752
	ds_write_b32 v172, v245 offset:11008
	ds_write_b32 v172, v246 offset:11264
	ds_write_b32 v172, v247 offset:11520
	ds_write_b32 v172, v248 offset:11776
	ds_write_b32 v172, v249 offset:12032
	s_waitcnt lgkmcnt(0)
	v_mul_u32_u24_e32 v1, 0xd0, v162
	v_lshlrev_b32_e32 v0, 4, v161
	v_add_u32_e32 v112, v1, v0
	v_lshlrev_b32_e32 v36, 6, v162
	v_sub_u32_e32 v176, v112, v36
	s_movk_i32 s13, 0x80
	s_cmp_lt_i32 s21, 1
	s_cselect_b32 s12, 0x2080, s13
	s_movk_i32 s13, 0x600
	v_add_u32_e32 v48, s12, v163
	v_mad_i64_i32 v[150:151], s[14:15], v48, s13, v[150:151]
	v_add_u32_e32 v48, s12, v164
	v_mad_i64_i32 v[154:155], s[14:15], v48, s13, v[154:155]
	s_lshl_b32 s12, s12, 1
	s_mov_b32 s13, 0
	v_lshl_add_u64 v[152:153], v[152:153], 0, s[12:13]
	v_readfirstlane_b32 s26, v150
	v_readfirstlane_b32 s27, v151
	v_readfirstlane_b32 s30, v152
	v_readfirstlane_b32 s31, v153
	s_nop 3
	v_subrev_u32_e32 v150, s26, v150
	v_subrev_u32_e32 v154, s26, v154
	v_subrev_u32_e32 v152, s30, v152
	v_add_u32_e32 v165, v165, v166
	v_add_u32_e32 v167, v167, v168
	v_add_u32_e32 v169, 0x6800, v169
	s_mov_b32 s14, 0xff800000
	s_mov_b32 s15, 0xff800000
	s_mov_b32 s28, 0
	v_mov_b32_e32 v0, 0
	v_mov_b32_e32 v1, 0
	v_mov_b32_e32 v2, 0
	v_mov_b32_e32 v3, 0
	v_mov_b32_e32 v4, 0
	v_mov_b32_e32 v5, 0
	v_mov_b32_e32 v6, 0
	v_mov_b32_e32 v7, 0
	v_mov_b32_e32 v8, 0
	v_mov_b32_e32 v9, 0
	v_mov_b32_e32 v10, 0
	v_mov_b32_e32 v11, 0
	v_mov_b32_e32 v12, 0
	v_mov_b32_e32 v13, 0
	v_mov_b32_e32 v14, 0
	v_mov_b32_e32 v15, 0
	v_mov_b32_e32 v16, 0
	v_mov_b32_e32 v17, 0
	v_mov_b32_e32 v18, 0
	v_mov_b32_e32 v19, 0
	v_mov_b32_e32 v20, 0
	v_mov_b32_e32 v21, 0
	v_mov_b32_e32 v22, 0
	v_mov_b32_e32 v23, 0
	v_mov_b32_e32 v24, 0
	v_mov_b32_e32 v25, 0
	v_mov_b32_e32 v26, 0
	v_mov_b32_e32 v27, 0
	v_mov_b32_e32 v28, 0
	v_mov_b32_e32 v29, 0
	v_mov_b32_e32 v30, 0
	v_mov_b32_e32 v31, 0
	v_mov_b32_e32 v32, 0
	v_mov_b32_e32 v33, 0
	v_mov_b32_e32 v34, 0
	v_mov_b32_e32 v35, 0
	v_mov_b32_e32 v36, 0
	v_mov_b32_e32 v37, 0
	v_mov_b32_e32 v38, 0
	v_mov_b32_e32 v39, 0
	v_mov_b32_e32 v40, 0
	v_mov_b32_e32 v41, 0
	v_mov_b32_e32 v42, 0
	v_mov_b32_e32 v43, 0
	v_mov_b32_e32 v44, 0
	v_mov_b32_e32 v45, 0
	v_mov_b32_e32 v46, 0
	v_mov_b32_e32 v47, 0
	v_mov_b32_e32 v156, 0
	v_mov_b32_e32 v157, 0
	v_readfirstlane_b32 s12, v170
	s_cmpk_ge_u32 s12, 0x100
	s_cbranch_scc1 .Lmla_B_entry
	.p2align	6
	s_nop 0
	s_nop 0
	s_nop 0
	s_nop 0
	s_nop 0
	s_nop 0
	s_nop 0
	s_nop 0
	s_nop 0
	s_nop 0

.Lmla_nopv_A:
	s_waitcnt lgkmcnt(11)
	v_mfma_f32_32x32x16_bf16 v[64:79], v[48:51], v[80:83], v[32:47]
	s_waitcnt lgkmcnt(10)
	v_mfma_f32_32x32x16_bf16 v[48:63], v[122:125], v[80:83], v[32:47]
	s_waitcnt lgkmcnt(9)
	v_mfma_f32_32x32x16_bf16 v[64:79], v[118:121], v[84:87], v[64:79]
	s_waitcnt lgkmcnt(8)
	v_mfma_f32_32x32x16_bf16 v[48:63], v[126:129], v[84:87], v[48:63]
	s_waitcnt lgkmcnt(7)
	v_mfma_f32_32x32x16_bf16 v[64:79], v[130:133], v[88:91], v[64:79]
	s_waitcnt lgkmcnt(6)
	v_mfma_f32_32x32x16_bf16 v[48:63], v[138:141], v[88:91], v[48:63]
	s_waitcnt lgkmcnt(5)
	v_mfma_f32_32x32x16_bf16 v[64:79], v[134:137], v[92:95], v[64:79]
	s_waitcnt lgkmcnt(4)
	v_mfma_f32_32x32x16_bf16 v[48:63], v[142:145], v[92:95], v[48:63]
	s_waitcnt lgkmcnt(3)
	v_mfma_f32_32x32x16_bf16 v[64:79], v[146:149], v[96:99], v[64:79]
	ds_read_b128 v[202:205], v177 offset:26624
	ds_read_b128 v[206:209], v177 offset:26656
	ds_read_b128 v[218:221], v177 offset:31232
	ds_read_b128 v[222:225], v177 offset:31264
	ds_read_b128 v[210:213], v177 offset:26688
	ds_read_b128 v[214:217], v177 offset:26720
	ds_read_b128 v[226:229], v177 offset:31296
	ds_read_b128 v[230:233], v177 offset:31328
	s_waitcnt lgkmcnt(10)
	v_mfma_f32_32x32x16_bf16 v[48:63], v[194:197], v[96:99], v[48:63]
	s_add_i32 s12, s28, 1
	s_cmp_ge_i32 s12, s22
	s_cbranch_scc1 .Lmla_nowrite_A
	s_waitcnt vmcnt(0)
	s_bitcmp1_b32 s12, 0
	s_cbranch_scc1 .Lmla_wodd_A
	ds_write_b128 v165, v[104:107]
	ds_write_b128 v167, v[108:111]
	ds_write_b64 v169, v[114:115]
	ds_write_b64 v169, v[116:117] offset:16
	s_branch .Lmla_wdone_A
.Lmla_wodd_A:
	ds_write_b128 v165, v[104:107] offset:13312
	ds_write_b128 v167, v[108:111] offset:13312
	ds_write_b64 v169, v[114:115] offset:9216
	ds_write_b64 v169, v[116:117] offset:9232
.Lmla_wdone_A:
	s_add_i32 s12, s28, 2
	s_cmp_ge_i32 s12, s22
	s_cbranch_scc1 .Lmla_nowrite_A
	s_nop 1
	global_load_dwordx4 v[104:107], v150, s[26:27]
	global_load_dwordx4 v[108:111], v154, s[26:27]
	global_load_dwordx4 v[114:117], v152, s[30:31]
	s_add_u32 s26, s26, 0x18000
	s_addc_u32 s27, s27, 0
	s_add_u32 s30, s30, 0x80
	s_addc_u32 s31, s31, 0

.Lmla_B_entry:
	s_and_b32 s12, s28, 1
	s_mul_i32 s13, s12, 0x3400
	v_add_u32_e32 v52, s13, v112
	ds_read_b128 v[48:51], v52
	ds_read_b128 v[122:125], v52 offset:6656
	ds_read_b128 v[118:121], v52 offset:32
	ds_read_b128 v[126:129], v52 offset:6688
	ds_read_b128 v[130:133], v52 offset:64
	ds_read_b128 v[138:141], v52 offset:6720
	ds_read_b128 v[134:137], v52 offset:96
	ds_read_b128 v[142:145], v52 offset:6752
	ds_read_b128 v[146:149], v52 offset:128
	ds_read_b128 v[194:197], v52 offset:6784
	ds_read_b128 v[178:181], v52 offset:160
	ds_read_b128 v[198:201], v52 offset:6816
	s_mul_i32 s13, s12, 0x2400
	v_add_u32_e32 v177, s13, v176
	s_setprio 3
	s_waitcnt lgkmcnt(11)
	v_mfma_f32_32x32x16_bf16 v[64:79], v[48:51], v[80:83], v[32:47]
	s_waitcnt lgkmcnt(10)
	v_mfma_f32_32x32x16_bf16 v[48:63], v[122:125], v[80:83], v[32:47]
	s_waitcnt lgkmcnt(9)
	v_mfma_f32_32x32x16_bf16 v[64:79], v[118:121], v[84:87], v[64:79]
	s_waitcnt lgkmcnt(8)
	v_mfma_f32_32x32x16_bf16 v[48:63], v[126:129], v[84:87], v[48:63]
	s_waitcnt lgkmcnt(7)
	v_mfma_f32_32x32x16_bf16 v[64:79], v[130:133], v[88:91], v[64:79]
	s_waitcnt lgkmcnt(6)
	v_mfma_f32_32x32x16_bf16 v[48:63], v[138:141], v[88:91], v[48:63]
	s_waitcnt lgkmcnt(5)
	v_mfma_f32_32x32x16_bf16 v[64:79], v[134:137], v[92:95], v[64:79]
	s_waitcnt lgkmcnt(4)
	v_mfma_f32_32x32x16_bf16 v[48:63], v[142:145], v[92:95], v[48:63]
	s_waitcnt lgkmcnt(3)
	v_mfma_f32_32x32x16_bf16 v[64:79], v[146:149], v[96:99], v[64:79]
	ds_read_b128 v[202:205], v177 offset:26624
	ds_read_b128 v[206:209], v177 offset:26656
	ds_read_b128 v[218:221], v177 offset:31232
	ds_read_b128 v[222:225], v177 offset:31264
	ds_read_b128 v[210:213], v177 offset:26688
	ds_read_b128 v[214:217], v177 offset:26720
	ds_read_b128 v[226:229], v177 offset:31296
	ds_read_b128 v[230:233], v177 offset:31328
	s_waitcnt lgkmcnt(10)
	v_mfma_f32_32x32x16_bf16 v[48:63], v[194:197], v[96:99], v[48:63]
	s_add_i32 s12, s28, 1
	s_cmp_ge_i32 s12, s22
	s_cbranch_scc1 .Lmla_nowrite_B0
	s_waitcnt vmcnt(0)
	s_bitcmp1_b32 s12, 0
	s_cbranch_scc1 .Lmla_wodd_B0
	ds_write_b128 v165, v[104:107]
	ds_write_b64 v169, v[114:115]
	ds_write_b64 v169, v[116:117] offset:16
	s_branch .Lmla_wdone_B0
.Lmla_wodd_B0:
	ds_write_b128 v165, v[104:107] offset:13312
	ds_write_b64 v169, v[114:115] offset:9216
	ds_write_b64 v169, v[116:117] offset:9232
.Lmla_wdone_B0:
	s_add_i32 s12, s28, 2
	s_cmp_ge_i32 s12, s22
	s_cbranch_scc1 .Lmla_nowrite_B0
	s_nop 1
	global_load_dwordx4 v[104:107], v150, s[26:27]
	global_load_dwordx4 v[114:117], v152, s[30:31]
	s_add_u32 s26, s26, 0x18000
	s_addc_u32 s27, s27, 0
	s_add_u32 s30, s30, 0x80
	s_addc_u32 s31, s31, 0

.Lmla_norescale_B:
	v_exp_f32_e32 v64, v64
	v_exp_f32_e32 v65, v65
	v_exp_f32_e32 v66, v66
	v_exp_f32_e32 v67, v67
	v_exp_f32_e32 v68, v68
	v_exp_f32_e32 v69, v69
	v_exp_f32_e32 v70, v70
	v_exp_f32_e32 v71, v71
	v_cvt_pk_bf16_f32 v234, v64, v65
	v_cvt_pk_bf16_f32 v235, v66, v67
	v_cvt_pk_bf16_f32 v236, v68, v69
	v_cvt_pk_bf16_f32 v237, v70, v71
	v_exp_f32_e32 v72, v72
	v_exp_f32_e32 v73, v73
	v_exp_f32_e32 v74, v74
	v_exp_f32_e32 v75, v75
	v_exp_f32_e32 v76, v76
	v_exp_f32_e32 v77, v77
	v_exp_f32_e32 v78, v78
	v_exp_f32_e32 v79, v79
	v_cvt_pk_bf16_f32 v238, v72, v73
	v_cvt_pk_bf16_f32 v239, v74, v75
	v_cvt_pk_bf16_f32 v240, v76, v77
	v_cvt_pk_bf16_f32 v241, v78, v79
	v_exp_f32_e32 v48, v48
	v_exp_f32_e32 v49, v49
	v_exp_f32_e32 v50, v50
	v_exp_f32_e32 v51, v51
	v_exp_f32_e32 v52, v52
	v_exp_f32_e32 v53, v53
	v_exp_f32_e32 v54, v54
	v_exp_f32_e32 v55, v55
	v_cvt_pk_bf16_f32 v242, v48, v49
	v_cvt_pk_bf16_f32 v243, v50, v51
	v_cvt_pk_bf16_f32 v244, v52, v53
	v_cvt_pk_bf16_f32 v245, v54, v55
	v_exp_f32_e32 v56, v56
	v_exp_f32_e32 v57, v57
	v_exp_f32_e32 v58, v58
	v_exp_f32_e32 v59, v59
	v_exp_f32_e32 v60, v60
	v_exp_f32_e32 v61, v61
	v_exp_f32_e32 v62, v62
	v_exp_f32_e32 v63, v63
	v_cvt_pk_bf16_f32 v246, v56, v57
	v_cvt_pk_bf16_f32 v247, v58, v59
	v_cvt_pk_bf16_f32 v248, v60, v61
	v_cvt_pk_bf16_f32 v249, v62, v63
	v_add_f32_e32 v172, v64, v65
	v_add_f32_e32 v173, v66, v67
	v_add_f32_e32 v177, v68, v69
	v_add_f32_e32 v64, v70, v71
	v_add_f32_e32 v172, v172, v72
	v_add_f32_e32 v173, v173, v73
	v_add_f32_e32 v177, v177, v74
	v_add_f32_e32 v64, v64, v75
	v_add_f32_e32 v172, v172, v76
	v_add_f32_e32 v173, v173, v77
	v_add_f32_e32 v177, v177, v78
	v_add_f32_e32 v64, v64, v79
	v_add_f32_e32 v172, v172, v48
	v_add_f32_e32 v173, v173, v49
	v_add_f32_e32 v177, v177, v50
	v_add_f32_e32 v64, v64, v51
	v_add_f32_e32 v172, v172, v52
	v_add_f32_e32 v173, v173, v53
	v_add_f32_e32 v177, v177, v54
	v_add_f32_e32 v64, v64, v55
	v_add_f32_e32 v172, v172, v56
	v_add_f32_e32 v173, v173, v57
	v_add_f32_e32 v177, v177, v58
	v_add_f32_e32 v64, v64, v59
	v_add_f32_e32 v172, v172, v60
	v_add_f32_e32 v173, v173, v61
	v_add_f32_e32 v177, v177, v62
	v_add_f32_e32 v64, v64, v63
	v_add_f32_e32 v172, v172, v173
	v_add_f32_e32 v177, v177, v64
	v_add_f32_e32 v172, v172, v177
	v_add_f32_e32 v157, v157, v172
	s_mov_b32 s14, 0x41000000
	s_mov_b32 s15, 0
	s_and_b32 s12, s28, 1
	s_mul_i32 s13, s12, 0x3400
	v_add_u32_e32 v52, s13, v112
	ds_read_b128 v[48:51], v52
	ds_read_b128 v[122:125], v52 offset:6656
	ds_read_b128 v[118:121], v52 offset:32
	ds_read_b128 v[126:129], v52 offset:6688
	ds_read_b128 v[130:133], v52 offset:64
	ds_read_b128 v[138:141], v52 offset:6720
	ds_read_b128 v[134:137], v52 offset:96
	ds_read_b128 v[142:145], v52 offset:6752
	ds_read_b128 v[146:149], v52 offset:128
	ds_read_b128 v[194:197], v52 offset:6784
	ds_read_b128 v[178:181], v52 offset:160
	ds_read_b128 v[198:201], v52 offset:6816
	s_mul_i32 s13, s12, 0x2400
	v_add_u32_e32 v177, s13, v176
	s_setprio 3
	v_mfma_f32_32x32x16_bf16 v[16:31], v[202:205], v[234:237], v[16:31]
	v_mfma_f32_32x32x16_bf16 v[0:15], v[218:221], v[234:237], v[0:15]
	v_mfma_f32_32x32x16_bf16 v[16:31], v[206:209], v[238:241], v[16:31]
	v_mfma_f32_32x32x16_bf16 v[0:15], v[222:225], v[238:241], v[0:15]
	v_mfma_f32_32x32x16_bf16 v[16:31], v[210:213], v[242:245], v[16:31]
	v_mfma_f32_32x32x16_bf16 v[0:15], v[226:229], v[242:245], v[0:15]
	v_mfma_f32_32x32x16_bf16 v[16:31], v[214:217], v[246:249], v[16:31]
	v_mfma_f32_32x32x16_bf16 v[0:15], v[230:233], v[246:249], v[0:15]
	s_waitcnt lgkmcnt(11)
	v_mfma_f32_32x32x16_bf16 v[64:79], v[48:51], v[80:83], v[32:47]
	s_waitcnt lgkmcnt(10)
	v_mfma_f32_32x32x16_bf16 v[48:63], v[122:125], v[80:83], v[32:47]
	s_waitcnt lgkmcnt(9)
	v_mfma_f32_32x32x16_bf16 v[64:79], v[118:121], v[84:87], v[64:79]
	s_waitcnt lgkmcnt(8)
	v_mfma_f32_32x32x16_bf16 v[48:63], v[126:129], v[84:87], v[48:63]
	s_waitcnt lgkmcnt(7)
	v_mfma_f32_32x32x16_bf16 v[64:79], v[130:133], v[88:91], v[64:79]
	s_waitcnt lgkmcnt(6)
	v_mfma_f32_32x32x16_bf16 v[48:63], v[138:141], v[88:91], v[48:63]
	s_waitcnt lgkmcnt(5)
	v_mfma_f32_32x32x16_bf16 v[64:79], v[134:137], v[92:95], v[64:79]
	s_waitcnt lgkmcnt(4)
	v_mfma_f32_32x32x16_bf16 v[48:63], v[142:145], v[92:95], v[48:63]
	s_waitcnt lgkmcnt(3)
	v_mfma_f32_32x32x16_bf16 v[64:79], v[146:149], v[96:99], v[64:79]
	ds_read_b128 v[202:205], v177 offset:26624
	ds_read_b128 v[206:209], v177 offset:26656
	ds_read_b128 v[218:221], v177 offset:31232
	ds_read_b128 v[222:225], v177 offset:31264
	ds_read_b128 v[210:213], v177 offset:26688
	ds_read_b128 v[214:217], v177 offset:26720
	ds_read_b128 v[226:229], v177 offset:31296
	ds_read_b128 v[230:233], v177 offset:31328
	s_waitcnt lgkmcnt(10)
	v_mfma_f32_32x32x16_bf16 v[48:63], v[194:197], v[96:99], v[48:63]
	s_add_i32 s12, s28, 1
	s_cmp_ge_i32 s12, s22
	s_cbranch_scc1 .Lmla_nowrite_B
	s_waitcnt vmcnt(0)
	s_bitcmp1_b32 s12, 0
	s_cbranch_scc1 .Lmla_wodd_B
	ds_write_b128 v165, v[104:107]
	ds_write_b64 v169, v[114:115]
	ds_write_b64 v169, v[116:117] offset:16
	s_branch .Lmla_wdone_B
